# k54 + mixers work-queue order: diff and DSA units interleaved 1:2 (index remap, same units, same work)
# speedup vs baseline: 1.0068x; 1.0068x over previous
; #define LAS __attribute__((address_space(3)))
; template <int MODE>
; DI void dense_unit(const Params& p, int l, int b, int n, LAS unsigned char* lds) {
;     ...
;   int tid_ = threadIdx.x; asm volatile("" : "+v"(tid_)); const int tid = tid_, lane = tid & 63, w = tid >> 6, r = lane & 31, h = lane >> 5, hd = w >> 1, qh = w & 1;
;   const u16* proj = (const u16*)(p.ws + WS_PROJ); u16* ybuf = (u16*)(p.ws + WS_XB);
;   const size_t tq = (size_t)b * S + n * 64 + qh * 32 + r;
;   const int iq = qh * 32 + r;
;   bf16x8 qf[4];
; #pragma unroll
;   for (int s = 0; s < 4; ++s) qf[s] = *(const bf16x8*)(proj + tq * NP + QCOL + hd * 64 + 16 * s + 8 * h);
;   LAS int* flag = (LAS int*)(lds + D_FLAG);
;   const int ntiles = n + 1;
;   u32x4 kr[4], vr[4];
;   {
;     const int m0 = (MODE == 2) ? n : 0; const u16* base = proj + ((size_t)b * S + m0 * 64) * NP;
; #pragma unroll
;     for (int i = 0; i < 4; ++i) { const int c = tid + 512 * i, row = c >> 5, c16 = c & 31; kr[i] = *(const u32x4*)(base + (size_t)row * NP + KCOL + c16 * 8); vr[i] = *(const u32x4*)(base + (size_t)row * NP + VCOL + c16 * 8); }
; #pragma unroll
;     for (int i = 0; i < 4; ++i) { const int c = tid + 512 * i, row = c >> 5, c16 = c & 31; *(LAS u32x4*)(lds + D_KOFF + row * D_RS + c16 * 16) = kr[i]; *(LAS u32x4*)(lds + D_VOFF + row * D_RS + c16 * 16) = vr[i]; }
;     if (tid < 3) flag[tid] = 0;
; __global__ void __launch_bounds__(512) hybrid_fwd(Params p) {
;     ...
;           if (tid == 0) *slot = (int)atomicAdd(ctl + l * 8 + bq, 1u);
;           __syncthreads();
;           const int idx = *slot;
;           __syncthreads();
;           if (idx >= MIX_UNITS_B) break;
;           if (idx < 4) ret_scan_unit(p, l, bq, idx, lds);
;           else if (idx < 132) dense256_unit<0>(p, l, bq, 31 - ((idx - 4) & 31), (idx - 4) >> 5, lds);
;           else if (idx < 388) dsa_unit(p, l, bq, 255 - (idx - 132), lds);
;           else dense_unit<2>(p, l, bq, 127 - (idx - 388), lds);
.LBB0_343:
	s_or_b64 exec, exec, s[6:7]
	v_mov_b32_e32 v0, s79
	s_waitcnt lgkmcnt(0)
	s_barrier
	ds_read_b32 v0, v0
	s_movk_i32 s2, 0x203
	s_mov_b64 s[6:7], -1
	s_waitcnt lgkmcnt(0)
	s_barrier
	v_cmp_lt_i32_e32 vcc, s2, v0
	v_readfirstlane_b32 s78, v0
	s_cbranch_vccnz .LBB0_338
	s_add_i32 s2, s78, -4
	s_cmpk_gt_u32 s2, 0x17f
	s_cbranch_scc1 .Lmy_noremap
	s_mul_hi_u32 s3, s2, 0xaaaaaaab
	s_lshr_b32 s3, s3, 1
	s_mul_i32 vcc_lo, s3, 3
	s_sub_i32 vcc_lo, s2, vcc_lo
	s_cmp_eq_u32 vcc_lo, 0
	s_cbranch_scc1 .Lmy_isdiff
	s_lshl_b32 s3, s3, 1
	s_add_i32 s3, s3, vcc_lo
	s_addk_i32 s3, 0x83
	s_mov_b32 s78, s3
	s_branch .Lmy_noremap
.Lmy_isdiff:
	s_add_i32 s78, s3, 4
.Lmy_noremap:
	s_cmp_gt_i32 s78, 3
	s_cbranch_scc0 .LBB0_978
	s_cmpk_gt_u32 s78, 0x83
	s_cbranch_scc0 .LBB0_964
	s_cmpk_gt_u32 s78, 0x183
	s_cbranch_scc0 .LBB0_362
	s_sub_i32 s79, 0x203, s78
	v_mov_b32_e32 v4, v168
	s_lshl_b32 s2, s79, 6
	v_and_b32_e32 v3, 31, v4
	v_lshrrev_b32_e32 v0, 1, v4
	s_add_i32 s6, s2, s0
	v_and_or_b32 v2, v0, 32, v3
	v_ashrrev_i32_e32 v0, 1, v4
	v_or_b32_e32 v114, s6, v2
	v_mov_b64_e32 v[6:7], s[56:57]
	s_waitcnt vmcnt(5)
	v_and_b32_e32 v100, 0xffffffc0, v0
	v_bfe_u32 v5, v4, 5, 1
	s_waitcnt vmcnt(4)
	v_mad_u64_u32 v[98:99], s[2:3], v114, s85, v[6:7]
	v_ashrrev_i32_e32 v101, 31, v100
	v_lshl_add_u64 v[6:7], v[100:101], 1, v[98:99]
	v_lshlrev_b32_e32 v0, 4, v5
	v_lshl_add_u64 v[6:7], v[6:7], 0, v[0:1]
	s_mov_b64 s[2:3], 0x1980
	s_movk_i32 s7, 0x1000
	s_mulk_i32 s6, 0x2200
	v_lshl_add_u64 v[8:9], v[6:7], 0, s[2:3]
	v_add_co_u32_e32 v6, vcc, s7, v6
	s_add_u32 s2, s56, s6
	s_nop 0
	v_addc_co_u32_e32 v7, vcc, 0, v7, vcc
	s_addc_u32 s3, s57, 0
	v_lshlrev_b32_e32 v0, 3, v4
	global_load_dwordx4 v[50:53], v[6:7], off offset:2432
	global_load_dwordx4 v[54:57], v[8:9], off offset:32
	global_load_dwordx4 v[58:61], v[8:9], off offset:64
	global_load_dwordx4 v[62:65], v[8:9], off offset:96
	v_and_b32_e32 v0, 0xf8, v0
	v_ashrrev_i32_e32 v6, 5, v4
	v_mov_b64_e32 v[10:11], s[2:3]
	v_mad_i64_i32 v[8:9], s[2:3], v6, s85, v[10:11]
	v_lshlrev_b32_e32 v0, 1, v0
	v_lshl_add_u64 v[8:9], v[8:9], 0, v[0:1]
	v_add_co_u32_e32 v8, vcc, s7, v8
	v_add_u32_e32 v7, 0x200, v4
	s_nop 0
	v_addc_co_u32_e32 v9, vcc, 0, v9, vcc
	v_ashrrev_i32_e32 v7, 5, v7
	global_load_dwordx4 v[66:69], v[8:9], off offset:2944
	global_load_dwordx4 v[70:73], v[8:9], off offset:3456
	v_mad_i64_i32 v[8:9], s[2:3], v7, s85, v[10:11]
	v_lshl_add_u64 v[8:9], v[8:9], 0, v[0:1]
	v_add_co_u32_e32 v8, vcc, s7, v8
	v_writelane_b32 v250, s90, 15
	s_nop 0
	v_addc_co_u32_e32 v9, vcc, 0, v9, vcc
	global_load_dwordx4 v[74:77], v[8:9], off offset:2944
	global_load_dwordx4 v[78:81], v[8:9], off offset:3456
	v_add_u32_e32 v8, 0x400, v4
	v_ashrrev_i32_e32 v8, 5, v8
	v_mad_i64_i32 v[12:13], s[2:3], v8, s85, v[10:11]
	v_add_u32_e32 v9, 0x600, v4
	v_lshl_add_u64 v[12:13], v[12:13], 0, v[0:1]
	v_ashrrev_i32_e32 v9, 5, v9
	v_add_co_u32_e32 v12, vcc, s7, v12
	v_mad_i64_i32 v[10:11], s[2:3], v9, s85, v[10:11]
	s_nop 0
	v_addc_co_u32_e32 v13, vcc, 0, v13, vcc
	v_lshl_add_u64 v[10:11], v[10:11], 0, v[0:1]
	global_load_dwordx4 v[82:85], v[12:13], off offset:2944
	global_load_dwordx4 v[86:89], v[12:13], off offset:3456
	v_add_co_u32_e32 v10, vcc, s7, v10
	s_movk_i32 s2, 0x210
	s_nop 0
	v_addc_co_u32_e32 v11, vcc, 0, v11, vcc
	global_load_dwordx4 v[90:93], v[10:11], off offset:2944
	global_load_dwordx4 v[94:97], v[10:11], off offset:3456
	v_lshlrev_b32_e32 v10, 4, v4
	v_and_b32_e32 v10, 0x1f0, v10
	v_add_u32_e32 v101, 0, v10
	v_mul_lo_u32 v116, v6, s2
	v_add_u32_e32 v115, s80, v10
	v_add_u32_e32 v10, v101, v116
	v_mul_lo_u32 v117, v7, s2
	v_mul_lo_u32 v118, v8, s2
	v_mul_lo_u32 v119, v9, s2
	s_movk_i32 s94, 0x1000
	v_cmp_gt_i32_e32 vcc, 3, v4
	v_writelane_b32 v250, s91, 16
	s_waitcnt vmcnt(7)
	ds_write_b128 v10, v[66:69]
	v_add_u32_e32 v10, v115, v116
	s_waitcnt vmcnt(6)
	ds_write_b128 v10, v[70:73]
	v_add_u32_e32 v10, v101, v117
	s_waitcnt vmcnt(5)
	ds_write_b128 v10, v[74:77]
	v_add_u32_e32 v10, v115, v117
	s_waitcnt vmcnt(4)
	ds_write_b128 v10, v[78:81]
	v_add_u32_e32 v10, v101, v118
	s_waitcnt vmcnt(3)
; #define LAS __attribute__((address_space(3)))
; DI float fexp2(float x) { return __builtin_amdgcn_exp2f(x); }
; DI float frcp(float x) { return __builtin_amdgcn_rcpf(x); }
; DI int crow(int i, int h) { return (i & 3) + 8 * (i >> 2) + 4 * h; }
; DI f32x16 zero16() { f32x16 z; for (int i = 0; i < 16; ++i) z[i] = 0.f; return z; }
; template <int MODE>
; DI void dense_unit(const Params& p, int l, int b, int n, LAS unsigned char* lds) {
;     ...
;     for (int i = 0; i < 4; ++i) { const int c = tid + 512 * i, row = c >> 5, c16 = c & 31; *(LAS u32x4*)(lds + D_KOFF + row * D_RS + c16 * 16) = kr[i]; *(LAS u32x4*)(lds + D_VOFF + row * D_RS + c16 * 16) = vr[i]; }
;     if (tid < 3) flag[tid] = 0;
;   }
;   __syncthreads();
;   f32x16 o1[2] = {zero16(), zero16()}, o2[2] = {zero16(), zero16()};
;   float l1 = 0.f, l2 = 0.f, carry = 1.0f;
;   const float lg2g = log2f(1.0f - exp2f(-5.0f - (float)hd));
;   const float cd = exp2f(lg2g * 64.0f);
;   (void)l2; (void)carry; (void)cd; (void)lg2g; (void)iq;
; #pragma unroll 1
;   for (int it = 0; it < ntiles; ++it) {
;     const int m = (MODE == 2) ? n - it : it, buf = it & 1; const bool has_next = it + 1 < ntiles;
;     ...
;           for (int i = 0; i < 16; ++i) { const float u = fexp2(sc[i]); float q = frcp(1.0f + u); if (diag) { const int jk = 32 * mt + crow(i, h); if (jk >= iq) q = 1.0f; } rr[i] = q; }
	ds_write_b128 v10, v[82:85]
	v_add_u32_e32 v10, v115, v118
	s_waitcnt vmcnt(2)
	ds_write_b128 v10, v[86:89]
	v_add_u32_e32 v10, v101, v119
	s_waitcnt vmcnt(1)
	ds_write_b128 v10, v[90:93]
	v_add_u32_e32 v10, v115, v119
	s_waitcnt vmcnt(0)
	ds_write_b128 v10, v[94:97]
	s_and_saveexec_b64 s[6:7], vcc
	v_lshl_add_u32 v10, v4, 2, 0
	v_add_u32_e32 v10, 0x21000, v10
	ds_write_b32 v10, v1
	s_mov_b64 s[90:91], s[56:57]
	s_or_b64 exec, exec, s[6:7]
	v_lshlrev_b32_e32 v120, 2, v5
	v_and_b32_e32 v10, 63, v4
	v_mad_i64_i32 v[102:103], s[2:3], v6, s85, 0
	v_mad_i64_i32 v[104:105], s[2:3], v7, s85, 0
	v_mad_i64_i32 v[106:107], s[2:3], v8, s85, 0
	v_and_b32_e32 v6, 0xffffff80, v4
	v_lshl_add_u32 v7, v5, 4, 0
	v_lshrrev_b32_e32 v5, 2, v4
	v_and_b32_e32 v8, 16, v4
	v_cmp_eq_u32_e64 s[10:11], 0, v4
	v_or_b32_e32 v4, 32, v120
	v_cmp_lt_u32_e64 s[12:13], v4, v2
	v_or_b32_e32 v4, 33, v120
	v_cmp_lt_u32_e64 s[14:15], v4, v2
	v_or_b32_e32 v4, 34, v120
	v_cmp_lt_u32_e64 s[16:17], v4, v2
	v_or_b32_e32 v4, 35, v120
	v_cmp_lt_u32_e64 s[18:19], v4, v2
	v_or_b32_e32 v4, 40, v120
	v_cmp_lt_u32_e64 s[20:21], v4, v2
	v_or_b32_e32 v4, 41, v120
	v_mad_i64_i32 v[108:109], s[2:3], v9, s85, 0
	v_lshlrev_b32_e32 v9, 2, v10
	v_cmp_lt_u32_e64 s[22:23], v4, v2
	v_or_b32_e32 v4, 42, v120
	v_and_b32_e32 v9, 12, v9
	v_cmp_lt_u32_e64 s[24:25], v4, v2
	v_or_b32_e32 v4, 43, v120
	v_or3_b32 v8, v8, v9, v100
	v_cmp_lt_u32_e64 s[26:27], v4, v2
	v_or_b32_e32 v4, 48, v120
	v_cmp_lt_u32_e64 s[28:29], v4, v2
	v_lshlrev_b32_e32 v4, 1, v8
	v_or_b32_e32 v8, 1, v120
	v_cmp_lt_u32_e64 s[48:49], v8, v2
	v_or_b32_e32 v8, 2, v120
	v_cmp_lt_u32_e64 s[50:51], v8, v2
	v_or_b32_e32 v8, 3, v120
	v_cmp_lt_u32_e64 s[52:53], v8, v2
	v_or_b32_e32 v8, 8, v120
	v_cmp_lt_u32_e64 s[54:55], v8, v2
	v_or_b32_e32 v8, 9, v120
	v_cmp_lt_u32_e64 s[56:57], v8, v2
	v_or_b32_e32 v8, 10, v120
	v_cmp_lt_u32_e64 s[58:59], v8, v2
	v_or_b32_e32 v8, 11, v120
	v_cmp_lt_u32_e64 s[60:61], v8, v2
	v_or_b32_e32 v8, 16, v120
	v_cmp_lt_u32_e64 s[62:63], v8, v2
	v_or_b32_e32 v8, 17, v120
	v_cmp_lt_u32_e64 s[64:65], v8, v2
	v_or_b32_e32 v8, 18, v120
	v_cmp_lt_u32_e64 s[66:67], v8, v2
	v_or_b32_e32 v8, 19, v120
	v_cmp_lt_u32_e64 s[68:69], v8, v2
	v_or_b32_e32 v8, 24, v120
	v_cmp_lt_u32_e64 s[70:71], v8, v2
	v_or_b32_e32 v8, 25, v120
	v_and_or_b32 v5, v5, 3, v120
	v_cmp_lt_u32_e64 s[72:73], v8, v2
	v_or_b32_e32 v8, 26, v120
	v_cmp_gt_u32_e64 s[6:7], 32, v10
	v_cmp_eq_u32_e64 s[8:9], 0, v10
	v_mul_u32_u24_e32 v3, 0x210, v3
	v_or_b32_e32 v9, 56, v120
	v_or_b32_e32 v10, 49, v120
	v_or_b32_e32 v11, 57, v120
	v_or_b32_e32 v12, 50, v120
	v_or_b32_e32 v13, 58, v120
	v_or_b32_e32 v14, 51, v120
	v_or_b32_e32 v15, 59, v120
	v_mul_u32_u24_e32 v5, 0x210, v5
	v_cmp_lt_u32_e64 s[74:75], v8, v2
	v_or_b32_e32 v8, 27, v120
	v_mov_b32_e32 v18, v1
	v_mov_b32_e32 v19, v1
	v_cmp_lt_u32_e64 s[30:31], v9, v2
	v_cmp_lt_u32_e64 s[34:35], v10, v2
	v_cmp_lt_u32_e64 s[36:37], v11, v2
	v_cmp_lt_u32_e64 s[38:39], v12, v2
	v_cmp_lt_u32_e64 s[40:41], v13, v2
	v_cmp_lt_u32_e64 s[42:43], v14, v2
	v_cmp_lt_u32_e64 s[44:45], v15, v2
	v_cmp_lt_u32_e64 s[46:47], v120, v2
	v_cmp_lt_u32_e64 s[76:77], v8, v2
	v_add3_u32 v121, v7, v6, v3
	v_add3_u32 v123, s80, v5, v4
	s_lshl_b32 s2, s78, 6
	v_mov_b32_e32 v20, v1
	v_mov_b32_e32 v21, v1
	v_mov_b32_e32 v22, v1
	v_mov_b32_e32 v23, v1
	v_mov_b32_e32 v24, v1
	v_mov_b32_e32 v25, v1
	v_mov_b32_e32 v26, v1
	v_mov_b32_e32 v27, v1
	v_mov_b32_e32 v28, v1
	v_mov_b32_e32 v29, v1
	v_mov_b32_e32 v30, v1
	v_mov_b32_e32 v31, v1
	v_mov_b32_e32 v32, v1
	v_mov_b32_e32 v33, v1
	v_mov_b64_e32 v[2:3], v[18:19]
	s_mov_b32 s84, 0
	s_sub_i32 s86, 0x204, s78
	s_mov_b32 s87, 1
	s_add_i32 s80, 0, 0x21000
	s_sub_i32 s93, 0x8080, s2
	v_mov_b32_e32 v110, 1.0
	v_readlane_b32 s81, v251, 41
	v_mov_b64_e32 v[4:5], v[20:21]
	v_mov_b64_e32 v[6:7], v[22:23]
	v_mov_b64_e32 v[8:9], v[24:25]
	v_mov_b64_e32 v[10:11], v[26:27]
	v_mov_b64_e32 v[12:13], v[28:29]
	v_mov_b64_e32 v[14:15], v[30:31]
	v_mov_b64_e32 v[16:17], v[32:33]
	s_waitcnt lgkmcnt(0)
	s_barrier
	s_branch .LBB0_351
